# attention tile loop: removed the lgkmcnt wait left behind the row-max permlane swap (no LDS operation is outstanding at that point)
# baseline (speedup 1.0000x reference)
; __device__ __forceinline__ unsigned pk_bf16(float lo, float hi) { unsigned r; asm("v_cvt_pk_bf16_f32 %0, %1, %2" : "=v"(r) : "v"(lo), "v"(hi)); return r; }
; __device__ void attn_item(const Params& p, int s_idx, char* smem) {
;     ...
;             float mx = sv[0];
; #pragma unroll
;             for (int i = 1; i < 32; ++i) mx = fmaxf(mx, sv[i]);
;             mx = fmaxf(mx, __shfl_xor(mx, 32));
;             const float mnew = fmaxf(mrun, mx);
;             const float alpha = __builtin_amdgcn_exp2f(mrun - mnew);
;             mrun = mnew;
;             float psum = 0.f;
; #pragma unroll
;             for (int i = 0; i < 32; ++i) { sv[i] = __builtin_amdgcn_exp2f(sv[i] - mnew); psum += sv[i]; }
;             lsum = lsum * alpha + psum;
; #pragma unroll
;             for (int i = 0; i < 16; ++i) { O0[i] *= alpha; O1[i] *= alpha; }
; #pragma unroll
;             for (int g = 0; g < 4; ++g) {
;                 bf16x8 pf;
;                 {
;                     const unsigned u0 = pk_bf16(sv[g * 8 + 0], sv[g * 8 + 1]), u1 = pk_bf16(sv[g * 8 + 2], sv[g * 8 + 3]);
;                     const unsigned u2 = pk_bf16(sv[g * 8 + 4], sv[g * 8 + 5]), u3 = pk_bf16(sv[g * 8 + 6], sv[g * 8 + 7]);
;                     const uint4 uu = {u0, u1, u2, u3};
;                     pf = __builtin_bit_cast(bf16x8, uu);
;                 }
;                 const int koff = (g >> 1) * 32 + (g & 1) * 16 + 8 * hh;
;                 const bf16x8 v0 = *(const bf16x8*)(sVt + ql * 72 + koff);
;                 const bf16x8 v1 = *(const bf16x8*)(sVt + (32 + ql) * 72 + koff);
;                 O0 = __builtin_amdgcn_mfma_f32_32x32x16_bf16(v0, pf, O0, 0, 0, 0);
;                 O1 = __builtin_amdgcn_mfma_f32_32x32x16_bf16(v1, pf, O1, 0, 0, 0);
.LBB0_113:
	s_or_b64 exec, exec, s[42:43]
	v_max_f32_e32 v40, v123, v123
	v_max_f32_e32 v41, v122, v122
	v_max_f32_e32 v40, v41, v40
	v_max3_f32 v40, v40, v120, v121
	v_max3_f32 v40, v40, v118, v119
	v_max3_f32 v40, v40, v54, v55
	v_max3_f32 v40, v40, v116, v117
	v_max3_f32 v40, v40, v50, v51
	v_max3_f32 v40, v40, v124, v125
	v_max3_f32 v40, v40, v60, v61
	v_max3_f32 v40, v40, v58, v59
	v_max3_f32 v40, v40, v52, v53
	v_max3_f32 v40, v40, v56, v57
	v_max3_f32 v40, v40, v48, v49
	v_max3_f32 v40, v40, v38, v39
	v_max3_f32 v40, v40, v34, v35
	v_max3_f32 v40, v40, v36, v37
	v_max3_f32 v40, v40, v32, v33
	v_mov_b32_e32 v41, v40
	s_nop 1
	v_permlane32_swap_b32_e32 v41, v40
	v_max_f32_e32 v42, v40, v41
	v_add_f32_e32 v43, 0xc3190000, v157
	v_cmp_lt_f32_e32 vcc, v42, v43
	s_andn2_b64 s[98:99], exec, vcc
	s_cbranch_scc0 .LBB0_114
	v_cmp_gt_f32_e32 vcc, v42, v157
	s_and_b64 s[98:99], exec, vcc
	v_max3_f32 v41, v157, v40, v41
	v_sub_f32_e32 v40, v122, v41
	v_exp_f32_e32 v62, v40
	v_sub_f32_e32 v40, v123, v41
	v_exp_f32_e32 v63, v40
	v_sub_f32_e32 v43, v120, v41
	v_exp_f32_e32 v120, v43
	v_sub_f32_e32 v43, v121, v41
	v_exp_f32_e32 v121, v43
	v_sub_f32_e32 v43, v118, v41
	v_add_f32_e32 v42, 0, v62
	v_exp_f32_e32 v118, v43
	v_sub_f32_e32 v43, v119, v41
	v_add_f32_e32 v42, v63, v42
	v_exp_f32_e32 v119, v43
	v_sub_f32_e32 v43, v54, v41
	v_add_f32_e32 v42, v120, v42
	v_exp_f32_e32 v122, v43
	v_sub_f32_e32 v43, v55, v41
	v_add_f32_e32 v42, v121, v42
	v_exp_f32_e32 v55, v43
	v_sub_f32_e32 v43, v116, v41
	v_add_f32_e32 v42, v118, v42
	v_exp_f32_e32 v116, v43
	v_sub_f32_e32 v43, v117, v41
	v_add_f32_e32 v42, v119, v42
	v_exp_f32_e32 v117, v43
	v_sub_f32_e32 v43, v50, v41
	v_add_f32_e32 v42, v122, v42
	v_exp_f32_e32 v123, v43
	v_sub_f32_e32 v43, v51, v41
	v_sub_f32_e32 v40, v157, v41
	v_add_f32_e32 v42, v55, v42
	v_exp_f32_e32 v157, v43
	v_sub_f32_e32 v43, v124, v41
	v_add_f32_e32 v42, v116, v42
	v_exp_f32_e32 v124, v43
	v_sub_f32_e32 v43, v125, v41
	v_add_f32_e32 v42, v117, v42
	v_exp_f32_e32 v125, v43
	v_add_f32_e32 v42, v123, v42
	v_add_f32_e32 v42, v157, v42
	v_add_f32_e32 v42, v124, v42
	v_add_f32_e32 v44, v125, v42
	v_sub_f32_e32 v42, v60, v41
	v_exp_f32_e32 v60, v42
	v_sub_f32_e32 v42, v61, v41
	v_exp_f32_e32 v61, v42
	v_sub_f32_e32 v42, v58, v41
	v_exp_f32_e32 v42, v42
	v_sub_f32_e32 v43, v59, v41
	v_exp_f32_e32 v43, v43
	v_add_f32_e32 v44, v60, v44
	v_add_f32_e32 v44, v61, v44
	v_add_f32_e32 v44, v42, v44
	v_add_f32_e32 v50, v43, v44
	v_sub_f32_e32 v44, v52, v41
	v_exp_f32_e32 v44, v44
	v_sub_f32_e32 v45, v53, v41
	v_exp_f32_e32 v45, v45
	v_sub_f32_e32 v46, v56, v41
	v_exp_f32_e32 v46, v46
	v_sub_f32_e32 v47, v57, v41
	v_exp_f32_e32 v47, v47
	v_add_f32_e32 v50, v44, v50
	v_add_f32_e32 v50, v45, v50
	v_sub_f32_e32 v48, v48, v41
	v_add_f32_e32 v50, v46, v50
	v_exp_f32_e32 v160, v48
	v_sub_f32_e32 v48, v49, v41
	v_add_f32_e32 v159, v47, v50
	v_exp_f32_e32 v161, v48
	ds_read_b64_tr_b16 v[48:49], v152 offset:9216
	ds_read_b64_tr_b16 v[50:51], v152 offset:9472
	ds_read_b64_tr_b16 v[56:57], v152 offset:13312
	ds_read_b64_tr_b16 v[58:59], v152 offset:13568
	v_exp_f32_e32 v40, v40
	v_cvt_pk_bf16_f32 v52, v62, v63
	v_cvt_pk_bf16_f32 v53, v120, v121
	v_cvt_pk_bf16_f32 v54, v118, v119
	v_cvt_pk_bf16_f32 v55, v122, v55
	v_sub_f32_e32 v38, v38, v41
	s_cmp_eq_u64 s[98:99], 0
	s_cbranch_scc1 .Lnr1a
	v_pk_mul_f32 v[14:15], v[14:15], v[40:41] op_sel_hi:[1,0]
	v_pk_mul_f32 v[12:13], v[12:13], v[40:41] op_sel_hi:[1,0]
	v_pk_mul_f32 v[10:11], v[10:11], v[40:41] op_sel_hi:[1,0]
	v_pk_mul_f32 v[8:9], v[8:9], v[40:41] op_sel_hi:[1,0]
	v_pk_mul_f32 v[6:7], v[6:7], v[40:41] op_sel_hi:[1,0]
	v_pk_mul_f32 v[4:5], v[4:5], v[40:41] op_sel_hi:[1,0]
	v_pk_mul_f32 v[2:3], v[2:3], v[40:41] op_sel_hi:[1,0]
	v_pk_mul_f32 v[0:1], v[0:1], v[40:41] op_sel_hi:[1,0]
	v_pk_mul_f32 v[30:31], v[30:31], v[40:41] op_sel_hi:[1,0]
	v_pk_mul_f32 v[28:29], v[28:29], v[40:41] op_sel_hi:[1,0]

; __device__ __forceinline__ unsigned pk_bf16(float lo, float hi) { unsigned r; asm("v_cvt_pk_bf16_f32 %0, %1, %2" : "=v"(r) : "v"(lo), "v"(hi)); return r; }
; __device__ void attn_item(const Params& p, int s_idx, char* smem) {
;     ...
;             float mx = sv[0];
; #pragma unroll
;             for (int i = 1; i < 32; ++i) mx = fmaxf(mx, sv[i]);
;             mx = fmaxf(mx, __shfl_xor(mx, 32));
;             const float mnew = fmaxf(mrun, mx);
;             const float alpha = __builtin_amdgcn_exp2f(mrun - mnew);
;             mrun = mnew;
;             float psum = 0.f;
; #pragma unroll
;             for (int i = 0; i < 32; ++i) { sv[i] = __builtin_amdgcn_exp2f(sv[i] - mnew); psum += sv[i]; }
;             lsum = lsum * alpha + psum;
; #pragma unroll
;             for (int i = 0; i < 16; ++i) { O0[i] *= alpha; O1[i] *= alpha; }
; #pragma unroll
;             for (int g = 0; g < 4; ++g) {
;                 bf16x8 pf;
;                 {
;                     const unsigned u0 = pk_bf16(sv[g * 8 + 0], sv[g * 8 + 1]), u1 = pk_bf16(sv[g * 8 + 2], sv[g * 8 + 3]);
;                     const unsigned u2 = pk_bf16(sv[g * 8 + 4], sv[g * 8 + 5]), u3 = pk_bf16(sv[g * 8 + 6], sv[g * 8 + 7]);
;                     const uint4 uu = {u0, u1, u2, u3};
;                     pf = __builtin_bit_cast(bf16x8, uu);
;                 }
;                 const int koff = (g >> 1) * 32 + (g & 1) * 16 + 8 * hh;
;                 const bf16x8 v0 = *(const bf16x8*)(sVt + ql * 72 + koff);
;                 const bf16x8 v1 = *(const bf16x8*)(sVt + (32 + ql) * 72 + koff);
;                 O0 = __builtin_amdgcn_mfma_f32_32x32x16_bf16(v0, pf, O0, 0, 0, 0);
;                 O1 = __builtin_amdgcn_mfma_f32_32x32x16_bf16(v1, pf, O1, 0, 0, 0);
.LBB0_119:
	s_or_b64 exec, exec, s[42:43]
	v_max_f32_e32 v40, v123, v123
	v_max_f32_e32 v41, v122, v122
	v_max_f32_e32 v40, v41, v40
	v_max3_f32 v40, v40, v120, v121
	v_max3_f32 v40, v40, v118, v119
	v_max3_f32 v40, v40, v54, v55
	v_max3_f32 v40, v40, v116, v117
	v_max3_f32 v40, v40, v50, v51
	v_max3_f32 v40, v40, v124, v125
	v_max3_f32 v40, v40, v60, v61
	v_max3_f32 v40, v40, v58, v59
	v_max3_f32 v40, v40, v52, v53
	v_max3_f32 v40, v40, v56, v57
	v_max3_f32 v40, v40, v48, v49
	v_max3_f32 v40, v40, v38, v39
	v_max3_f32 v40, v40, v34, v35
	v_max3_f32 v40, v40, v36, v37
	v_max3_f32 v40, v40, v32, v33
	v_mov_b32_e32 v41, v40
	s_nop 1
	v_permlane32_swap_b32_e32 v41, v40
	v_max_f32_e32 v42, v40, v41
	v_add_f32_e32 v43, 0xc3190000, v157
	v_cmp_lt_f32_e32 vcc, v42, v43
	s_andn2_b64 s[98:99], exec, vcc
	s_cbranch_scc0 .LBB0_120
	v_cmp_gt_f32_e32 vcc, v42, v157
	s_and_b64 s[98:99], exec, vcc
	v_max3_f32 v41, v157, v40, v41
	v_sub_f32_e32 v40, v122, v41
	v_exp_f32_e32 v62, v40
	v_sub_f32_e32 v40, v123, v41
	v_exp_f32_e32 v63, v40
	v_sub_f32_e32 v43, v120, v41
	v_exp_f32_e32 v120, v43
	v_sub_f32_e32 v43, v121, v41
	v_exp_f32_e32 v121, v43
	v_sub_f32_e32 v43, v118, v41
	v_add_f32_e32 v42, 0, v62
	v_exp_f32_e32 v118, v43
	v_sub_f32_e32 v43, v119, v41
	v_add_f32_e32 v42, v63, v42
	v_exp_f32_e32 v119, v43
	v_sub_f32_e32 v43, v54, v41
	v_add_f32_e32 v42, v120, v42
	v_exp_f32_e32 v122, v43
	v_sub_f32_e32 v43, v55, v41
	v_add_f32_e32 v42, v121, v42
	v_exp_f32_e32 v55, v43
	v_sub_f32_e32 v43, v116, v41
	v_add_f32_e32 v42, v118, v42
	v_exp_f32_e32 v116, v43
	v_sub_f32_e32 v43, v117, v41
	v_add_f32_e32 v42, v119, v42
	v_exp_f32_e32 v117, v43
	v_sub_f32_e32 v43, v50, v41
	v_add_f32_e32 v42, v122, v42
	v_exp_f32_e32 v123, v43
	v_sub_f32_e32 v43, v51, v41
	v_sub_f32_e32 v40, v157, v41
	v_add_f32_e32 v42, v55, v42
	v_exp_f32_e32 v157, v43
	v_sub_f32_e32 v43, v124, v41
	v_add_f32_e32 v42, v116, v42
	v_exp_f32_e32 v124, v43
	v_sub_f32_e32 v43, v125, v41
	v_add_f32_e32 v42, v117, v42
	v_exp_f32_e32 v125, v43
	v_add_f32_e32 v42, v123, v42
	v_add_f32_e32 v42, v157, v42
	v_add_f32_e32 v42, v124, v42
	v_add_f32_e32 v44, v125, v42
	v_sub_f32_e32 v42, v60, v41
	v_exp_f32_e32 v60, v42
	v_sub_f32_e32 v42, v61, v41
	v_exp_f32_e32 v61, v42
	v_sub_f32_e32 v42, v58, v41
	v_exp_f32_e32 v42, v42
	v_sub_f32_e32 v43, v59, v41
	v_exp_f32_e32 v43, v43
	v_add_f32_e32 v44, v60, v44
	v_add_f32_e32 v44, v61, v44
	v_add_f32_e32 v44, v42, v44
	v_add_f32_e32 v50, v43, v44
	v_sub_f32_e32 v44, v52, v41
	v_exp_f32_e32 v44, v44
	v_sub_f32_e32 v45, v53, v41
	v_exp_f32_e32 v45, v45
	v_sub_f32_e32 v46, v56, v41
	v_exp_f32_e32 v46, v46
	v_sub_f32_e32 v47, v57, v41
	v_exp_f32_e32 v47, v47
	v_add_f32_e32 v50, v44, v50
	v_add_f32_e32 v50, v45, v50
	v_sub_f32_e32 v48, v48, v41
	v_add_f32_e32 v50, v46, v50
	v_exp_f32_e32 v160, v48
	v_sub_f32_e32 v48, v49, v41
	v_add_f32_e32 v159, v47, v50
	v_exp_f32_e32 v161, v48
	ds_read_b64_tr_b16 v[48:49], v152 offset:27904
	ds_read_b64_tr_b16 v[50:51], v152 offset:28160
	ds_read_b64_tr_b16 v[56:57], v152 offset:32000
	ds_read_b64_tr_b16 v[58:59], v152 offset:32256
	v_exp_f32_e32 v40, v40
	v_cvt_pk_bf16_f32 v52, v62, v63
	v_cvt_pk_bf16_f32 v53, v120, v121
	v_cvt_pk_bf16_f32 v54, v118, v119
	v_cvt_pk_bf16_f32 v55, v122, v55
	v_sub_f32_e32 v38, v38, v41
	s_cmp_eq_u64 s[98:99], 0
	s_cbranch_scc1 .Lnr1b
	v_pk_mul_f32 v[14:15], v[14:15], v[40:41] op_sel_hi:[1,0]
	v_pk_mul_f32 v[12:13], v[12:13], v[40:41] op_sel_hi:[1,0]
	v_pk_mul_f32 v[10:11], v[10:11], v[40:41] op_sel_hi:[1,0]
	v_pk_mul_f32 v[8:9], v[8:9], v[40:41] op_sel_hi:[1,0]
	v_pk_mul_f32 v[6:7], v[6:7], v[40:41] op_sel_hi:[1,0]
	v_pk_mul_f32 v[4:5], v[4:5], v[40:41] op_sel_hi:[1,0]
	v_pk_mul_f32 v[2:3], v[2:3], v[40:41] op_sel_hi:[1,0]
	v_pk_mul_f32 v[0:1], v[0:1], v[40:41] op_sel_hi:[1,0]
	v_pk_mul_f32 v[30:31], v[30:31], v[40:41] op_sel_hi:[1,0]
	v_pk_mul_f32 v[28:29], v[28:29], v[40:41] op_sel_hi:[1,0]
